# v13 + weight-conversion work re-cut: prologue converts 12800 items (was 28032), GEMM-tail slots up to 8 items per idle wave
# speedup vs baseline: 1.0045x; 1.0045x over previous
.LBB0_79:
	s_add_i32 s6, s6, s94
	s_cmpk_lt_i32 s6, 0x3200
	s_cbranch_scc0 .LBB0_145
.LBB0_80:
	s_add_i32 s0, s6, 0x16600
	s_cmpk_lt_i32 s6, 0x2c00
	s_cselect_b32 s4, s6, s0
	s_cmpk_lt_i32 s4, 0x2000
	s_cbranch_scc1 .LBB0_123
	s_cmpk_gt_u32 s4, 0x2fff
	s_mov_b64 s[2:3], -1
	s_cbranch_scc0 .LBB0_119
	s_cmpk_gt_u32 s4, 0x71ff
	s_cbranch_scc0 .LBB0_116
	s_cmpk_gt_u32 s4, 0x79ff
	s_cbranch_scc0 .LBB0_113
	s_cmpk_gt_u32 s4, 0x89ff
	s_cbranch_scc0 .LBB0_110
	s_cmpk_gt_u32 s4, 0xcbff
	s_cbranch_scc0 .LBB0_107
	s_cmpk_gt_u32 s4, 0xebff
	s_cbranch_scc0 .LBB0_104
	s_cmpk_gt_u32 s4, 0xfbff
	s_cbranch_scc0 .LBB0_101
	s_cmp_gt_u32 s4, 0x13dff
	s_cbranch_scc0 .LBB0_98
	s_cmp_gt_u32 s4, 0x145ff
	s_cbranch_scc0 .LBB0_95
	s_cmp_gt_u32 s4, 0x155ff
	s_cbranch_scc0 .LBB0_92
	s_add_i32 s5, s4, 0xffffd000
	s_mov_b64 s[2:3], 0

.LBB0_379:
	s_or_b64 exec, exec, s[36:37]
	v_readlane_b32 s24, v251, 2
	v_readlane_b32 s26, v251, 4
	v_readlane_b32 s27, v251, 5
	s_add_u32 s42, s26, 0x23c00000
	s_addc_u32 s43, s27, 0
	s_add_u32 s44, s26, 0x1b800000
	s_addc_u32 s45, s27, 0
	s_add_u32 s70, s26, 0xc00000
	s_addc_u32 s71, s27, 0
	s_cmpk_lt_i32 s84, 0x840
	s_cselect_b64 s[72:73], -1, 0
	s_ashr_i32 s47, s84, 31
	s_lshr_b32 s0, s47, 29
	s_add_i32 s0, s84, s0
	s_ashr_i32 s31, s0, 3
	s_and_b32 s0, s0, -8
	s_sub_i32 s33, s84, s0
	s_ashr_i32 s97, s96, 31
	s_add_u32 s29, s26, 0x1500000
	s_addc_u32 s83, s27, 0
	s_add_u32 s8, s26, 0x30400000
	s_addc_u32 s9, s27, 0
	s_min_i32 s0, s84, 0x83f
	s_ashr_i32 s1, s0, 31
	s_lshr_b32 s1, s1, 28
	s_add_i32 s1, s0, s1
	s_and_b32 s2, s1, 0xfffff0
	s_sub_i32 s4, s0, s2
	s_lshl_b32 s0, s1, 3
	s_and_b32 s0, s0, 0xffffff80
	s_ashr_i32 s1, s0, 31
	s_lshl_b64 s[2:3], s[0:1], 13
	s_add_u32 s6, s8, s2
	v_writelane_b32 v252, s8, 0
	s_addc_u32 s7, s9, s3
	s_lshl_b32 s4, s4, 8
	s_ashr_i32 s5, s4, 31
	s_lshl_b64 s[4:5], s[4:5], 1
	s_add_u32 s6, s6, s4
	s_addc_u32 s7, s7, s5
	v_writelane_b32 v252, s9, 1
	s_add_u32 s8, s6, 0x20000
	s_addc_u32 s9, s7, 0
	v_writelane_b32 v252, s8, 32
	s_mov_b32 s28, s12
	s_movk_i32 s93, 0x16c
	v_writelane_b32 v252, s9, 33
	s_add_u32 s8, s6, 0x40000
	s_addc_u32 s9, s7, 0
	v_writelane_b32 v252, s8, 34
	v_readlane_b32 s25, v251, 3
	v_mov_b32_e32 v203, 0
	v_writelane_b32 v252, s9, 35
	s_add_u32 s8, s6, 0x60000
	s_addc_u32 s9, s7, 0
	v_writelane_b32 v252, s8, 36
	v_mov_b32_e32 v0, 0x260
	v_mov_b32_e32 v236, 0x40666666
	v_writelane_b32 v252, s9, 37
	s_add_u32 s8, s6, 0x80000
	s_addc_u32 s9, s7, 0
	v_writelane_b32 v252, s8, 38
	v_mbcnt_hi_u32_b32 v237, -1, v69
	s_movk_i32 s89, 0x4000
	v_writelane_b32 v252, s9, 39
	s_add_u32 s8, s6, 0xa0000
	s_addc_u32 s9, s7, 0
	v_writelane_b32 v252, s8, 40
	s_mov_b32 s77, 0xffff0000
	s_mov_b32 s51, 0xc0666666
	v_writelane_b32 v252, s9, 41
	s_add_u32 s8, s6, 0xc0000
	s_addc_u32 s9, s7, 0
	v_writelane_b32 v252, s8, 42
	s_movk_i32 s53, 0x7fff
	s_mov_b32 s67, 0x2801000
	v_writelane_b32 v252, s9, 43
	s_add_u32 s8, s6, 0xe0000
	v_writelane_b32 v252, s6, 44
	s_addc_u32 s9, s7, 0
	s_add_u32 s78, s26, 0x28000000
	v_writelane_b32 v252, s7, 45
	s_addc_u32 s79, s27, 0
	s_lshl_b64 s[0:1], s[0:1], 3
	v_writelane_b32 v252, s8, 46
	s_add_u32 s0, s29, s0
	s_addc_u32 s1, s83, s1
	v_writelane_b32 v252, s9, 47
	v_writelane_b32 v252, s0, 48
	s_mov_b32 s87, 0
	s_mov_b64 s[80:81], 0x80
	v_writelane_b32 v252, s1, 49
	s_add_u32 s0, s78, s2
	s_addc_u32 s1, s79, s3
	s_add_u32 s0, s0, s4
	s_addc_u32 s1, s1, s5
	s_add_u32 s2, s0, 0x20000
	s_addc_u32 s3, s1, 0
	v_writelane_b32 v252, s2, 50
	s_mov_b32 s74, 0x3e8e38e4
	s_mov_b32 s76, 0x3f35102b
	v_writelane_b32 v252, s3, 51
	s_add_u32 s2, s0, 0x40000
	s_addc_u32 s3, s1, 0
	v_writelane_b32 v252, s2, 52
	s_mov_b32 s46, 0x406095ad
	s_mov_b32 s48, 0xc0f75c23
	v_writelane_b32 v252, s3, 53
	s_add_u32 s2, s0, 0x60000
	s_addc_u32 s3, s1, 0
	v_writelane_b32 v252, s2, 54
	s_mov_b32 s50, 0x4122bf24
	s_mov_b32 s92, 0xc1124633
	v_writelane_b32 v252, s3, 55
	s_add_u32 s2, s0, 0x80000
	s_addc_u32 s3, s1, 0
	v_writelane_b32 v252, s2, 56
	s_mov_b32 s82, 0x40c2591c
	s_mov_b32 s52, 0xc04719c3
	v_writelane_b32 v252, s3, 57
	s_add_u32 s2, s0, 0xa0000
	s_addc_u32 s3, s1, 0
	v_writelane_b32 v252, s2, 58
	s_mov_b32 s54, 0x3fb7d0d5
	s_waitcnt lgkmcnt(0)
	v_writelane_b32 v252, s3, 59
	s_add_u32 s2, s0, 0xc0000
	s_addc_u32 s3, s1, 0
	v_writelane_b32 v252, s2, 60
	s_barrier
	s_nop 0
	v_writelane_b32 v252, s3, 61
	s_add_u32 s2, s0, 0xe0000
	v_writelane_b32 v252, s0, 62
	s_addc_u32 s3, s1, 0
	v_writelane_b32 v253, s2, 0
	s_cmpk_lt_i32 s84, 0x200
	v_writelane_b32 v252, s1, 63
	v_writelane_b32 v253, s3, 1
	s_cselect_b64 s[0:1], -1, 0
	s_lshl_b32 s2, s33, 6
	s_add_u32 s68, s26, 0x46e00000
	s_addc_u32 s69, s27, 0
	v_writelane_b32 v253, s0, 2
	s_cmpk_lt_i32 s84, 0x80
	s_nop 0
	v_writelane_b32 v253, s1, 3
	s_cselect_b64 s[0:1], -1, 0
	v_writelane_b32 v253, s0, 4
	s_and_b32 s30, s84, 7
	s_nop 0
	v_writelane_b32 v253, s1, 5
	s_bfe_u32 s0, s84, 0x10003
	s_or_b32 s3, s0, 64
	s_lshl_b32 s0, s84, 6
	s_and_b32 s4, s0, 0xfffffc00
	s_lshl_b32 s0, s3, 21
	s_ashr_i32 s5, s4, 31
	s_lshl_b32 s1, s30, 21
	s_add_u32 s0, s78, s0
	v_writelane_b32 v253, s1, 6
	s_addc_u32 s1, s79, 0
	s_add_u32 s0, s0, s4
	s_addc_u32 s1, s1, s5
	s_add_u32 s6, s0, 0x100000
	v_writelane_b32 v253, s0, 7
	s_addc_u32 s7, s1, 0
	s_cmpk_lt_i32 s84, 0xb58
	v_writelane_b32 v253, s1, 8
	v_writelane_b32 v253, s6, 9
	s_cselect_b64 s[0:1], -1, 0
	s_cmpk_lt_i32 s84, 0xb0
	v_writelane_b32 v253, s7, 10
	v_writelane_b32 v253, s0, 11
	s_cselect_b64 s[6:7], -1, 0
	s_nop 0
	v_writelane_b32 v253, s1, 12
	s_mul_i32 s0, s3, 0x2c0000
	v_writelane_b32 v253, s3, 13
	s_add_u32 s0, s78, s0
	v_writelane_b32 v253, s6, 14
	s_addc_u32 s1, s79, 0
	s_add_u32 s0, s0, s4
	v_writelane_b32 v253, s7, 15
	v_writelane_b32 v253, s4, 16
	s_addc_u32 s1, s1, s5
	v_writelane_b32 v253, s5, 17
	s_add_u32 s4, s0, 0x160000
	v_writelane_b32 v253, s0, 18
	s_addc_u32 s5, s1, 0
	s_movk_i32 s3, 0x43
	v_writelane_b32 v253, s1, 19
	s_add_u32 s0, s26, 0x30000000
	s_addc_u32 s1, s27, 0
	v_writelane_b32 v253, s4, 20
	v_writelane_b32 v252, s0, 26
	s_cmpk_lt_i32 s84, 0x210
	v_writelane_b32 v253, s5, 21
	v_writelane_b32 v252, s1, 27
	s_cselect_b64 s[0:1], -1, 0
	v_writelane_b32 v253, s0, 22
	s_cmpk_lt_i32 s56, 0x200
	v_readlane_b32 s8, v252, 10
	v_writelane_b32 v253, s1, 23
	s_cselect_b64 s[0:1], -1, 0
	s_ashr_i32 s4, s56, 2
	v_writelane_b32 v253, s0, 24
	s_ashr_i32 s5, s4, 31
	s_ashr_i32 s57, s56, 31
	v_writelane_b32 v253, s1, 25
	s_lshl_b64 s[0:1], s[4:5], 17
	v_writelane_b32 v253, s0, 26
	v_readlane_b32 s20, v252, 22
	v_readlane_b32 s21, v252, 23
	v_writelane_b32 v253, s1, 27
	s_lshl_b64 s[0:1], s[56:57], 18
	s_add_u32 s0, s78, s0
	s_addc_u32 s1, s79, s1
	s_add_u32 s6, s0, 0x20000
	v_writelane_b32 v253, s0, 28
	s_addc_u32 s7, s1, 0
	s_cmpk_lt_i32 s56, 0x80
	v_writelane_b32 v253, s1, 29
	v_writelane_b32 v253, s6, 30
	s_cselect_b64 s[0:1], -1, 0
	v_readlane_b32 s14, v252, 16
	v_writelane_b32 v253, s7, 31
	v_writelane_b32 v253, s0, 32
	v_readlane_b32 s15, v252, 17
	v_readlane_b32 s16, v252, 18
	v_writelane_b32 v253, s1, 33
	s_add_u32 s0, s26, 0x34400000
	s_addc_u32 s1, s27, 0
	v_writelane_b32 v253, s0, 34
	s_add_u32 s64, s26, 0x34800000
	s_addc_u32 s65, s27, 0
	v_writelane_b32 v253, s1, 35
	s_mov_b32 s0, s4
	v_writelane_b32 v253, s0, 36
	v_readlane_b32 s9, v252, 11
	v_readlane_b32 s10, v252, 12
	v_writelane_b32 v253, s1, 37
	s_lshl_b64 s[0:1], s[4:5], 18
	v_writelane_b32 v253, s0, 38
	v_readlane_b32 s11, v252, 13
	v_readlane_b32 s13, v252, 15
	v_writelane_b32 v253, s1, 39
	s_add_u32 s0, s20, 0x4000
	s_addc_u32 s1, s21, 0
	v_writelane_b32 v253, s0, 40
	s_cmp_lt_i32 s33, 0
	v_readlane_b32 s12, v252, 14
	v_writelane_b32 v253, s1, 41
	s_cselect_b64 s[0:1], -1, 0
	v_writelane_b32 v253, s0, 42
	v_readlane_b32 s17, v252, 19
	v_readlane_b32 s18, v252, 20
	v_writelane_b32 v253, s1, 43
	s_and_b64 s[0:1], s[0:1], exec
	s_movk_i32 s1, 0x109
	s_cselect_b32 s1, s1, 0x108
	s_mul_i32 s0, s33, 0x41
	s_mul_i32 s1, s33, s1
	s_cselect_b32 s0, s0, s2
	s_cselect_b32 s2, s93, 0x16b
	s_cselect_b32 s3, s3, 0x42
	s_add_i32 s1, s1, s31
	s_ashr_i32 s4, s1, 31
	s_lshr_b32 s4, s4, 24
	s_add_i32 s4, s1, s4
	s_and_b32 s5, s4, 0xffffff00
	s_add_i32 s0, s0, s31
	s_sub_i32 s5, s1, s5
	s_ashr_i32 s1, s0, 31
	s_lshr_b32 s1, s1, 26
	s_add_i32 s1, s0, s1
	s_and_b32 s6, s1, 0xffc0
	s_sub_i32 s0, s0, s6
	s_bfe_i32 s6, s0, 0x80000
	s_bfe_u32 s6, s6, 0x3000c
	s_add_i32 s6, s0, s6
	s_and_b32 s7, s6, 0xf8
	s_sub_i32 s0, s0, s7
	s_ashr_i32 s1, s1, 6
	s_bfe_i32 s6, s6, 0x80000
	s_lshl_b32 s1, s1, 3
	s_sext_i32_i16 s6, s6
	s_sext_i32_i8 s0, s0
	s_add_i32 s14, s1, s0
	s_lshr_b32 s0, s6, 3
	s_ashr_i32 s4, s4, 8
	s_bfe_i64 s[0:1], s[0:1], 0x100000
	s_lshl_b32 s4, s4, 3
	s_lshl_b64 s[0:1], s[0:1], 21
	s_sub_i32 s7, 0x42, s4
	s_ashr_i32 s15, s14, 31
	v_writelane_b32 v253, s0, 44
	s_min_u32 s7, s7, 8
	s_ashr_i32 s16, s6, 3
	v_writelane_b32 v253, s1, 45
	s_lshl_b64 s[0:1], s[14:15], 21
	s_add_u32 s0, s78, s0
	s_addc_u32 s1, s79, s1
	s_add_u32 s8, s0, 0x100000
	v_writelane_b32 v253, s0, 46
	s_addc_u32 s9, s1, 0
	s_mov_b32 s10, s14
	v_writelane_b32 v253, s1, 47
	s_mul_i32 s0, s33, s2
	s_add_i32 s0, s0, s31
	s_mul_hi_i32 s1, s0, 0x2e8ba2e9
	s_lshr_b32 s2, s1, 31
	s_ashr_i32 s1, s1, 6
	s_add_i32 s1, s1, s2
	v_writelane_b32 v253, s8, 48
	s_mul_i32 s2, s1, 0x160
	s_lshl_b32 s6, s1, 3
	v_writelane_b32 v253, s9, 49
	s_sub_i32 s2, s0, s2
	s_sub_i32 s0, 0x42, s6
	s_min_u32 s8, s0, 8
	v_writelane_b32 v253, s10, 50
	s_mul_i32 s1, s14, 0x2c0000
	s_mul_hi_i32 s0, s14, 0x2c0000
	v_writelane_b32 v253, s11, 51
	s_add_u32 s10, s78, s1
	s_addc_u32 s11, s79, s0
	s_add_u32 s0, s10, 0x160000
	v_writelane_b32 v253, s10, 52
	s_addc_u32 s1, s11, 0
	v_cvt_f32_ubyte0_e32 v2, s7
	v_writelane_b32 v253, s11, 53
	v_writelane_b32 v253, s0, 54
	v_cvt_f32_i32_e32 v1, s5
	v_rcp_iflag_f32_e32 v3, v2
	v_writelane_b32 v253, s1, 55
	s_mul_i32 s0, s33, s3
	s_add_i32 s0, s0, s31
	s_ashr_i32 s1, s0, 31
	s_lshr_b32 s1, s1, 26
	s_add_i32 s1, s0, s1
	s_and_b32 s3, s1, 0xffffffc0
	s_sub_i32 s9, s0, s3
	s_ashr_i32 s0, s1, 6
	s_lshl_b32 s10, s0, 3
	v_mul_f32_e32 v3, v1, v3
	s_sub_i32 s0, 0x42, s10
	v_trunc_f32_e32 v3, v3
	s_min_u32 s11, s0, 8
	s_ashr_i32 s0, s5, 30
	v_fma_f32 v1, -v3, v2, v1
	s_or_b32 s3, s0, 1
	v_cmp_ge_f32_e64 s[0:1], |v1|, v2
	v_cvt_i32_f32_e32 v1, v3
	s_and_b64 s[0:1], s[0:1], exec
	s_cselect_b32 s0, s3, 0
	v_writelane_b32 v253, s33, 56
	v_readfirstlane_b32 s1, v1
	s_add_i32 s13, s1, s0
	s_mul_i32 s0, s13, s7
	s_abs_i32 s7, s96
	v_cvt_f32_u32_e32 v1, s7
	s_sub_i32 s0, s5, s0
	s_sext_i32_i16 s0, s0
	v_writelane_b32 v253, s31, 57
	v_rcp_iflag_f32_e32 v1, v1
	s_add_i32 s0, s4, s0
	v_writelane_b32 v253, s0, 58
	s_sub_i32 s0, 0, s7
	v_mul_f32_e32 v1, 0x4f7ffffe, v1
	v_cvt_u32_f32_e32 v1, v1
	v_cvt_f32_ubyte0_e32 v2, s8
	v_rcp_iflag_f32_e32 v3, v2
	v_readlane_b32 s19, v252, 21
	v_readfirstlane_b32 s1, v1
	s_mul_i32 s0, s0, s1
	s_mul_hi_u32 s0, s1, s0
	s_add_i32 s14, s1, s0
	s_mul_hi_u32 s0, s14, 0x840
	s_mul_i32 s0, s0, s7
	s_sub_i32 s0, 0x840, s0
	s_sub_i32 s1, s0, s7
	s_cmp_ge_u32 s0, s7
	s_cselect_b32 s0, s1, s0
	s_sub_i32 s1, s0, s7
	s_cmp_ge_u32 s0, s7
	s_cselect_b32 s0, s1, s0
	s_sub_i32 s1, s96, s0
	s_sub_i32 s0, s84, s0
	v_cvt_f32_i32_e32 v1, s2
	s_cmp_gt_i32 s0, -1
	s_cselect_b64 s[4:5], -1, 0
	v_writelane_b32 v253, s4, 59
	s_lshl_b32 s0, s0, 3
	v_mul_f32_e32 v3, v1, v3
	v_writelane_b32 v253, s5, 60
	v_writelane_b32 v253, s0, 61
	s_lshl_b32 s0, s1, 3
	v_trunc_f32_e32 v3, v3
	v_writelane_b32 v253, s0, 62
	s_ashr_i32 s0, s2, 30
	v_fma_f32 v1, -v3, v2, v1
	s_or_b32 s3, s0, 1
	v_cmp_ge_f32_e64 s[0:1], |v1|, v2
	v_cvt_i32_f32_e32 v1, v3
	s_and_b64 s[0:1], s[0:1], exec
	s_cselect_b32 s0, s3, 0
	v_cvt_f32_ubyte0_e32 v2, s11
	v_readfirstlane_b32 s1, v1
	s_add_i32 s0, s1, s0
	s_mul_i32 s1, s0, s8
	s_sub_i32 s1, s2, s1
	s_sext_i32_i16 s1, s1
	s_bfe_i64 s[2:3], s[0:1], 0x100000
	s_lshl_b64 s[2:3], s[2:3], 20
	s_add_i32 s4, s6, s1
	v_writelane_b32 v253, s2, 63
	s_ashr_i32 s5, s4, 31
	s_mul_hi_u32 s1, s14, 0xb58
	v_writelane_b32 v254, s3, 0
	s_mov_b32 s2, s4
	v_writelane_b32 v254, s2, 1
	s_mul_i32 s1, s1, s7
	v_cvt_f32_i32_e32 v1, s9
	v_writelane_b32 v254, s3, 2
	s_lshl_b64 s[2:3], s[4:5], 20
	s_add_u32 s2, s42, s2
	s_addc_u32 s3, s43, s3
	s_add_u32 s4, s2, 0x80000
	v_writelane_b32 v254, s2, 3
	s_addc_u32 s5, s3, 0
	s_sub_i32 s1, 0xb58, s1
	v_writelane_b32 v254, s3, 4
	s_sub_i32 s2, s1, s7
	s_cmp_ge_u32 s1, s7
	s_cselect_b32 s1, s2, s1
	s_sub_i32 s2, s1, s7
	v_rcp_iflag_f32_e32 v3, v2
	s_cmp_ge_u32 s1, s7
	s_cselect_b32 s1, s2, s1
	s_sub_i32 s2, s96, s1
	s_sub_i32 s3, s84, s1
	v_writelane_b32 v254, s4, 5
	s_cmp_gt_i32 s3, -1
	v_mul_f32_e32 v3, v1, v3
	v_writelane_b32 v254, s5, 6
	s_cselect_b64 s[4:5], -1, 0
	v_trunc_f32_e32 v3, v3
	v_writelane_b32 v254, s4, 7
	s_lshl_b32 s8, s2, 3
	s_ashr_i32 s2, s9, 30
	v_fma_f32 v1, -v3, v2, v1
	v_writelane_b32 v254, s5, 8
	s_lshl_b32 s6, s3, 3
	s_or_b32 s4, s2, 1
	v_cmp_ge_f32_e64 s[2:3], |v1|, v2
	v_cvt_i32_f32_e32 v1, v3
	s_and_b64 s[2:3], s[2:3], exec
	s_cselect_b32 s2, s4, 0
	s_sext_i32_i16 s0, s0
	v_readfirstlane_b32 s3, v1
	s_add_i32 s2, s3, s2
	s_mul_i32 s3, s2, s11
	s_sub_i32 s3, s9, s3
	s_sext_i32_i8 s3, s3
	s_bfe_i64 s[4:5], s[2:3], 0x80000
	s_lshl_b64 s[4:5], s[4:5], 20
	s_add_i32 s10, s10, s3
	v_writelane_b32 v254, s4, 9
	s_ashr_i32 s11, s10, 31
	v_readlane_b32 s22, v252, 24
	v_writelane_b32 v254, s5, 10
	s_mov_b32 s4, s10
	v_writelane_b32 v254, s4, 11
	v_readlane_b32 s23, v252, 25
	s_mov_b32 s12, s29
	v_writelane_b32 v254, s5, 12
	s_lshl_b64 s[4:5], s[10:11], 20
	s_add_u32 s4, s42, s4
	v_writelane_b32 v254, s0, 13
	s_sext_i32_i8 s0, s2
	s_addc_u32 s5, s43, s5
	v_writelane_b32 v254, s0, 14
	s_add_u32 s2, s4, 0x80000
	v_writelane_b32 v254, s4, 15
	s_mul_hi_u32 s0, s14, 0x210
	s_addc_u32 s3, s5, 0
	v_writelane_b32 v254, s5, 16
	s_mul_i32 s0, s0, s7
	v_writelane_b32 v254, s2, 17
	s_sub_i32 s0, 0x210, s0
	v_mov_b32_e32 v1, 1
	v_writelane_b32 v254, s3, 18
	s_sub_i32 s2, s0, s7
	s_cmp_ge_u32 s0, s7
	s_cselect_b32 s0, s2, s0
	s_sub_i32 s2, s0, s7
	s_cmp_ge_u32 s0, s7
	s_cselect_b32 s0, s2, s0
	s_sub_i32 s2, s96, s0
	s_sub_i32 s0, s84, s0
	s_cmp_gt_i32 s0, -1
	s_cselect_b64 s[4:5], -1, 0
	v_writelane_b32 v254, s4, 19
	s_lshl_b32 s0, s0, 3
	s_nop 0
	v_writelane_b32 v254, s5, 20
	v_writelane_b32 v254, s0, 21
	s_lshl_b32 s0, s2, 3
	v_writelane_b32 v254, s0, 22
	s_mul_hi_u32 s0, s14, 0x420
	s_mul_i32 s0, s0, s7
	s_sub_i32 s0, 0x420, s0
	s_sub_i32 s2, s0, s7
	s_cmp_ge_u32 s0, s7
	s_cselect_b32 s0, s2, s0
	s_sub_i32 s2, s0, s7
	s_cmp_ge_u32 s0, s7
	s_cselect_b32 s0, s2, s0
	s_sub_i32 s2, s96, s0
	s_sub_i32 s0, s84, s0
	s_cmp_gt_i32 s0, -1
	s_cselect_b64 s[4:5], -1, 0
	v_writelane_b32 v254, s4, 23
	s_lshl_b32 s0, s0, 3
	s_add_i32 s0, s0, 0xc200
	v_writelane_b32 v254, s5, 24
	v_writelane_b32 v254, s0, 25
	s_lshl_b32 s0, s2, 3
	v_writelane_b32 v254, s0, 26
	v_writelane_b32 v254, s6, 27
	s_add_i32 s0, s6, 0xec00
	s_ashr_i32 s95, s94, 31
	v_writelane_b32 v254, s0, 28
	s_ashr_i32 s0, s28, 31
	v_writelane_b32 v254, s0, 29
	s_lshl_b32 s0, s84, 8
	s_lshl_b64 s[2:3], s[94:95], 3
	v_writelane_b32 v254, s0, 30
	s_lshl_b32 s0, s84, 7
	v_writelane_b32 v252, s2, 28
	v_writelane_b32 v254, s0, 31
	s_lshl_b32 s0, s56, 5
	v_writelane_b32 v252, s3, 29
	s_lshl_b64 s[2:3], s[94:95], 9
	s_lshl_b32 s75, s96, 4
	v_writelane_b32 v254, s0, 32
	s_lshl_b32 s0, s96, 5
	v_writelane_b32 v252, s2, 8
	v_writelane_b32 v254, s0, 33
	s_nop 0
	v_writelane_b32 v252, s3, 9
	s_add_u32 s2, s26, 0x44c00100
	s_addc_u32 s3, s27, 0
	v_writelane_b32 v254, s2, 34
	s_lshl_b32 s0, s56, 4
	s_lshl_b64 s[62:63], s[96:97], 17
	v_writelane_b32 v254, s3, 35
	s_add_u32 s2, s26, 0x40c00200
	v_writelane_b32 v254, s0, 36
	s_addc_u32 s3, s27, 0
	v_writelane_b32 v254, s2, 37
	s_lshl_b32 s0, s1, 3
	s_lshl_b32 s1, s84, 3
	v_writelane_b32 v254, s3, 38
	s_sub_i32 s0, s1, s0
	s_sext_i32_i16 s1, s13
	v_writelane_b32 v254, s1, 39
	s_add_i32 s0, s0, 0xd400
	v_writelane_b32 v254, s0, 40
	v_writelane_b32 v254, s30, 41
	s_mul_i32 s0, s30, 0x2c0000
	v_writelane_b32 v254, s0, 42
	s_mul_hi_i32 s0, s16, 0x2c0000
	v_writelane_b32 v254, s0, 43
	v_writelane_b32 v254, s16, 44
	s_mul_i32 s0, s16, 0x2c0000
	v_writelane_b32 v254, s0, 45
	s_lshl_b64 s[0:1], s[96:97], 18
	v_writelane_b32 v254, s0, 46
	v_writelane_b32 v251, s62, 62
	s_movk_i32 s13, 0x2c00
	v_writelane_b32 v254, s1, 47
	s_add_u32 s0, s24, 0x1000
	v_writelane_b32 v254, s0, 48
	s_addc_u32 s0, s25, 0
	v_writelane_b32 v254, s0, 49
	v_writelane_b32 v254, s28, 50
	s_add_i32 s0, s28, s94
	v_writelane_b32 v254, s0, 51
	s_add_i32 s0, 0, 0x20160
	v_writelane_b32 v254, s0, 52
	s_add_i32 s0, 0, 0x20164
	v_writelane_b32 v254, s0, 53
	s_add_i32 s0, 0, 0x1a800
	v_writelane_b32 v254, s0, 54
	s_add_i32 s0, 0, 0x1aa00
	v_writelane_b32 v254, s0, 55
	s_add_i32 s0, 0, 0x10800
	v_writelane_b32 v254, s0, 56
	s_add_i32 s0, 0, 0x1a900
	v_writelane_b32 v254, s0, 57
	s_mov_b32 s0, 0
	v_writelane_b32 v254, s0, 58
	s_lshl_b64 s[0:1], s[94:95], 13
	v_writelane_b32 v254, s0, 60
	v_writelane_b32 v251, s63, 63
	s_nop 0
	v_writelane_b32 v254, s1, 61
	s_lshl_b64 s[0:1], s[94:95], 12
	v_writelane_b32 v254, s0, 62
	s_mov_b32 s95, s8
	s_nop 0
	v_writelane_b32 v254, s1, 63
	s_mov_b64 s[0:1], -1
	v_writelane_b32 v255, s0, 0
	s_nop 1
	v_writelane_b32 v255, s1, 1
	v_writelane_b32 v255, s83, 2
	v_writelane_b32 v255, s95, 3
	v_writelane_b32 v255, s72, 4
	s_nop 1
	v_writelane_b32 v255, s73, 5
	s_branch .LBB0_383

.LBB0_473:
	v_readlane_b32 s0, v255, 0
	v_readlane_b32 s1, v255, 1
	s_and_b64 s[0:1], s[0:1], exec
	s_movk_i32 s0, 0x5c00
	s_cselect_b32 s95, s0, 0x13e00
	v_readlane_b32 s0, v253, 59
	s_waitcnt lgkmcnt(0)
	v_mov_b32_e32 v4, v56
	v_readlane_b32 s1, v253, 60
	s_andn2_b64 vcc, exec, s[0:1]
	v_readfirstlane_b32 s0, v4
	s_cbranch_vccnz .LBB0_529
	v_readlane_b32 s2, v255, 0
	v_readlane_b32 s3, v255, 1
	s_and_b64 s[2:3], s[2:3], exec
	s_movk_i32 s1, 0x2c00
	s_cselect_b32 s1, s1, 0x11600
	s_ashr_i32 s0, s0, 6
	s_add_i32 s1, s0, s1
	v_readlane_b32 s2, v253, 61
	s_add_i32 s6, s1, s2
	s_cmp_ge_i32 s6, s95
	s_cbranch_scc1 .LBB0_529
	s_lshl_b32 s0, s0, 14
	v_bfe_u32 v3, v4, 5, 1
	v_and_b32_e32 v2, 31, v4
	v_bfe_u32 v12, v4, 3, 3
	v_lshlrev_b32_e32 v4, 3, v4
	s_add_i32 s0, s0, 0
	v_lshlrev_b32_e32 v5, 2, v2
	v_mul_u32_u24_e32 v6, 0x84, v3
	v_and_b32_e32 v4, 56, v4
	v_add3_u32 v5, s0, v5, v6
	v_mul_u32_u24_e32 v6, 0x84, v4
	v_lshlrev_b32_e32 v7, 2, v12
	v_add3_u32 v13, s0, v6, v7
	v_readlane_b32 s0, v251, 50
	v_lshlrev_b32_e32 v202, 1, v4
	v_readlane_b32 s1, v251, 51
	v_or_b32_e32 v14, 8, v12
	v_or_b32_e32 v15, 16, v12
	v_or_b32_e32 v16, 24, v12
	v_lshl_add_u64 v[6:7], s[0:1], 0, v[202:203]
	s_branch .LBB0_477

.LBB0_844:
	v_readlane_b32 s0, v255, 0
	v_readlane_b32 s1, v255, 1
	s_and_b64 s[0:1], s[0:1], exec
	s_mov_b32 s0, 0x8600
	s_cselect_b32 s93, s0, 0x15600
	v_readlane_b32 s0, v254, 7
	v_readlane_b32 s1, v254, 8
	v_mov_b32_e32 v4, v56
	s_andn2_b64 vcc, exec, s[0:1]
	v_cndmask_b32_e64 v2, 0, 1, s[0:1]
	v_cmp_ne_u32_e64 s[2:3], 1, v2
	v_readfirstlane_b32 s0, v4
	s_nop 0
	v_writelane_b32 v255, s2, 10
	s_nop 1
	v_writelane_b32 v255, s3, 11
	s_cbranch_vccnz .LBB0_908
	s_ashr_i32 s0, s0, 6
	s_add_i32 s1, s0, s95
	v_readlane_b32 s2, v254, 27
	s_add_i32 s6, s1, s2
	s_cmp_ge_i32 s6, s93
	s_cbranch_scc1 .LBB0_908
	s_lshl_b32 s0, s0, 14
	v_bfe_u32 v3, v4, 5, 1
	v_and_b32_e32 v2, 31, v4
	v_bfe_u32 v10, v4, 3, 3
	v_lshlrev_b32_e32 v4, 3, v4
	s_add_i32 s0, s0, 0
	v_lshlrev_b32_e32 v5, 2, v2
	v_mul_u32_u24_e32 v6, 0x84, v3
	v_and_b32_e32 v4, 56, v4
	v_add3_u32 v5, s0, v5, v6
	v_mul_u32_u24_e32 v6, 0x84, v4
	v_lshlrev_b32_e32 v7, 2, v10
	v_add3_u32 v11, s0, v6, v7
	v_or_b32_e32 v12, 8, v10
	v_or_b32_e32 v13, 16, v10
	v_or_b32_e32 v14, 24, v10
	v_readlane_b32 s15, v255, 3
	s_movk_i32 s33, 0x4000
	s_branch .LBB0_848

.LBB0_1122:
	v_readlane_b32 s0, v254, 19
	v_mov_b32_e32 v4, v56
	v_readlane_b32 s1, v254, 20
	s_andn2_b64 vcc, exec, s[0:1]
	v_readfirstlane_b32 s0, v4
	s_cbranch_vccnz .LBB0_1190
	v_readlane_b32 s2, v255, 0
	v_readlane_b32 s3, v255, 1
	s_and_b64 s[2:3], s[2:3], exec
	s_mov_b32 s1, 0x19200
	s_cselect_b32 s6, 0xc200, s1
	s_ashr_i32 s0, s0, 6
	s_add_i32 s1, s0, s93
	v_readlane_b32 s2, v254, 21
	s_add_i32 s7, s1, s2
	s_cmp_ge_i32 s7, s6
	s_cbranch_scc1 .LBB0_1190
	s_lshl_b32 s0, s0, 14
	v_bfe_u32 v3, v4, 5, 1
	v_and_b32_e32 v2, 31, v4
	v_bfe_u32 v10, v4, 3, 3
	v_lshlrev_b32_e32 v4, 3, v4
	s_add_i32 s0, s0, 0
	v_lshlrev_b32_e32 v5, 2, v2
	v_mul_u32_u24_e32 v6, 0x84, v3
	v_and_b32_e32 v4, 56, v4
	v_add3_u32 v5, s0, v5, v6
	v_mul_u32_u24_e32 v6, 0x84, v4
	v_lshlrev_b32_e32 v7, 2, v10
	v_add3_u32 v11, s0, v6, v7
	v_or_b32_e32 v12, 8, v10
	v_or_b32_e32 v13, 16, v10
	v_or_b32_e32 v14, 24, v10
	v_readlane_b32 s33, v254, 22
	s_branch .LBB0_1126

.LBB0_1435:
	v_readlane_b32 s0, v255, 0
	v_readlane_b32 s1, v255, 1
	s_andn2_b64 vcc, exec, s[0:1]
	s_nop 0
	v_cndmask_b32_e64 v2, 0, 1, s[0:1]
	v_cmp_ne_u32_e64 s[6:7], 1, v2
	s_cbranch_vccnz .LBB0_1484
	v_readlane_b32 s0, v254, 23
	v_mov_b32_e32 v4, v56
	v_readlane_b32 s1, v254, 24
	s_andn2_b64 vcc, exec, s[0:1]
	v_readfirstlane_b32 s0, v4
	s_cbranch_vccnz .LBB0_1484
	s_ashr_i32 s0, s0, 6
	v_readlane_b32 s1, v254, 25
	s_add_i32 s8, s0, s1
	s_cmp_gt_i32 s8, 0xebff
	s_cbranch_scc1 .LBB0_1484
	s_lshl_b32 s0, s0, 14
	v_bfe_u32 v3, v4, 5, 1
	v_and_b32_e32 v2, 31, v4
	v_bfe_u32 v12, v4, 3, 3
	v_lshlrev_b32_e32 v4, 3, v4
	s_add_i32 s0, s0, 0
	v_lshlrev_b32_e32 v5, 2, v2
	v_mul_u32_u24_e32 v6, 0x84, v3
	v_and_b32_e32 v4, 56, v4
	v_add3_u32 v5, s0, v5, v6
	v_mul_u32_u24_e32 v6, 0x84, v4
	v_lshlrev_b32_e32 v7, 2, v12
	v_add3_u32 v13, s0, v6, v7
	v_readlane_b32 s0, v251, 50
	v_lshlrev_b32_e32 v202, 1, v4
	v_readlane_b32 s1, v251, 51
	v_or_b32_e32 v14, 8, v12
	v_or_b32_e32 v15, 16, v12
	v_or_b32_e32 v16, 24, v12
	v_lshl_add_u64 v[6:7], s[0:1], 0, v[202:203]
	s_branch .LBB0_1440
.LBB0_1439:
	v_readlane_b32 s0, v254, 26
	s_add_i32 s8, s8, s0
	s_cmp_lt_i32 s8, 0xec00
	s_cbranch_scc0 .LBB0_1484

.LBB0_1601:
	s_and_b64 vcc, exec, s[6:7]
	s_movk_i32 s93, 0x16c
	s_cbranch_vccnz .LBB0_1656
	v_readlane_b32 s0, v255, 10
	v_mov_b32_e32 v4, v56
	v_readlane_b32 s1, v255, 11
	s_and_b64 vcc, exec, s[0:1]
	v_readfirstlane_b32 s0, v4
	s_cbranch_vccnz .LBB0_1656
	s_ashr_i32 s0, s0, 6
	v_readlane_b32 s1, v254, 28
	s_add_i32 s8, s0, s1
	s_cmp_gt_i32 s8, 0x115ff
	s_cbranch_scc1 .LBB0_1656
	s_lshl_b32 s1, s0, 14
	v_bfe_u32 v3, v4, 5, 1
	v_and_b32_e32 v2, 31, v4
	v_bfe_u32 v12, v4, 3, 3
	v_lshlrev_b32_e32 v4, 3, v4
	s_add_i32 s1, s1, 0
	v_lshlrev_b32_e32 v5, 2, v2
	v_mul_u32_u24_e32 v6, 0x84, v3
	v_and_b32_e32 v4, 56, v4
	v_add3_u32 v5, s1, v5, v6
	v_mul_u32_u24_e32 v6, 0x84, v4
	v_lshlrev_b32_e32 v7, 2, v12
	v_readlane_b32 s2, v251, 50
	v_add3_u32 v13, s1, v6, v7
	v_lshlrev_b32_e32 v202, 1, v4
	v_readlane_b32 s3, v251, 51
	v_readlane_b32 s1, v254, 40
	v_or_b32_e32 v14, 8, v12
	v_or_b32_e32 v15, 16, v12
	v_or_b32_e32 v16, 24, v12
	v_lshl_add_u64 v[6:7], s[2:3], 0, v[202:203]
	s_add_i32 s9, s1, s0
	s_branch .LBB0_1606
.LBB0_1605:
	s_add_i32 s9, s9, s95
	s_add_i32 s8, s8, s95
	s_add_i32 s0, s9, 0x1800
	s_cmp_lt_i32 s0, 0x11600
	s_cbranch_scc0 .LBB0_1656
